# ring combine: LDS slot flags polled/released with DS ops instead of flat ops (no vmcnt drain per poll); loader waves use counted vmcnt waits so two steps stay in flight
# speedup vs baseline: 1.0135x; 1.0032x over previous
.LBB0_398:
	s_andn2_b64 vcc, exec, s[0:1]
	s_cbranch_vccnz .LBB0_473
	s_mov_b64 s[0:1], s[88:89]
	v_mbcnt_lo_u32_b32 v0, -1, 0
	v_mbcnt_hi_u32_b32 v0, -1, v0
	s_nop 0
	v_add_u32_e32 v0, s29, v0
	s_load_dwordx2 s[0:1], s[0:1], 0xa8
	v_cmp_gt_i32_e32 vcc, 10, v0
	s_waitcnt lgkmcnt(0)
	s_barrier
	s_and_saveexec_b64 s[4:5], vcc
	s_cbranch_execz .LBB0_401
	s_mov_b64 s[6:7], src_shared_base
	s_add_i32 s6, 0, 0x1e000
	s_waitcnt vmcnt(15)
	v_lshl_add_u32 v4, v0, 2, s6
	v_mov_b32_e32 v5, s7
	ds_write_b32 v4, v3
	s_waitcnt lgkmcnt(0)

.LBB0_407:
	s_add_i32 s4, s72, 7
	s_cmp_lt_i32 s72, 56
	s_cselect_b64 s[6:7], -1, 0
	s_cmp_gt_i32 s72, 55
	s_cbranch_scc1 .LBB0_409
	s_ashr_i32 s5, s4, 31
	s_lshl_b64 s[8:9], s[4:5], 15
	s_add_u32 s8, s70, s8
	s_addc_u32 s9, s71, s9
	v_lshl_add_u64 v[64:65], s[8:9], 0, v[2:3]

	v_add_co_u32_e32 v48, vcc, 0x1000, v64
	global_load_dwordx4 v[40:43], v[64:65], off
	global_load_dwordx4 v[36:39], v[64:65], off offset:2048
	v_addc_co_u32_e32 v49, vcc, 0, v65, vcc
	v_add_co_u32_e32 v56, vcc, 0x2000, v64
	v_lshl_add_u64 v[92:93], s[8:9], 0, v[0:1]
	s_nop 0
	v_addc_co_u32_e32 v57, vcc, 0, v65, vcc
	v_add_co_u32_e32 v64, vcc, 0x3000, v64
	global_load_dwordx4 v[52:55], v[48:49], off
	s_nop 0
	global_load_dwordx4 v[48:51], v[48:49], off offset:2048
	v_addc_co_u32_e32 v65, vcc, 0, v65, vcc
	v_add_co_u32_e32 v80, vcc, 0x4000, v92
	global_load_dwordx4 v[60:63], v[56:57], off
	s_nop 0
	global_load_dwordx4 v[56:59], v[56:57], off offset:2048
	v_addc_co_u32_e32 v81, vcc, 0, v93, vcc
	v_add_co_u32_e32 v84, vcc, 0x5000, v92
	global_load_dwordx4 v[68:71], v[64:65], off
	s_nop 0
	global_load_dwordx4 v[64:67], v[64:65], off offset:2048
	v_addc_co_u32_e32 v85, vcc, 0, v93, vcc
	v_add_co_u32_e32 v94, vcc, 0x6000, v92
	global_load_dwordx4 v[80:83], v[80:81], off
	s_nop 0
	global_load_dwordx4 v[84:87], v[84:85], off
	v_addc_co_u32_e32 v95, vcc, 0, v93, vcc
	v_add_co_u32_e32 v96, vcc, 0x7000, v92
	s_nop 1
	v_addc_co_u32_e32 v97, vcc, 0, v93, vcc
	global_load_dwordx4 v[92:95], v[94:95], off
	s_nop 0
	global_load_dwordx4 v[96:99], v[96:97], off
.LBB0_409:
	s_mov_b64 s[8:9], src_shared_base
	s_mul_hi_i32 s5, s72, 0x66666667
	s_lshr_b32 s8, s5, 31
	s_ashr_i32 s5, s5, 2
	s_add_i32 s5, s5, s8
	s_mul_i32 s8, s5, 10
	s_sub_i32 s73, s72, s8
	s_lshl_b32 s8, s73, 2
	s_add_i32 s8, s8, 0
	s_add_i32 s8, s8, 0x1e000
	v_mov_b64_e32 v[102:103], s[8:9]
	ds_read_b32 v102, v102

	s_lshl_b32 s5, s5, 1
	s_waitcnt lgkmcnt(0)
	v_cmp_ne_u32_e32 vcc, s5, v102
	s_and_saveexec_b64 s[10:11], vcc
	s_cbranch_execz .LBB0_426
	s_mov_b32 s74, 0xffff8
	s_mov_b64 s[20:21], 0
	s_branch .LBB0_418

.LBB0_418:
	v_mov_b64_e32 v[102:103], s[8:9]
	s_sleep 1
	ds_read_b32 v102, v102

	s_or_b64 s[34:35], s[34:35], exec
	s_waitcnt lgkmcnt(0)
	v_cmp_ne_u32_e32 vcc, s5, v102
	s_and_saveexec_b64 s[36:37], vcc
	s_cbranch_execz .LBB0_417
	v_mov_b64_e32 v[102:103], s[8:9]
	s_sleep 1
	ds_read_b32 v102, v102

	s_mov_b64 s[42:43], -1
	s_waitcnt lgkmcnt(0)
	v_cmp_ne_u32_e32 vcc, s5, v102
	s_and_saveexec_b64 s[40:41], vcc
	s_cbranch_execz .LBB0_416
	v_mov_b64_e32 v[102:103], s[8:9]
	s_sleep 1
	ds_read_b32 v102, v102

	s_mov_b64 s[44:45], -1
	s_waitcnt lgkmcnt(0)
	v_cmp_ne_u32_e32 vcc, s5, v102
	s_and_saveexec_b64 s[42:43], vcc
	s_cbranch_execz .LBB0_415
	v_mov_b64_e32 v[102:103], s[8:9]
	s_sleep 1
	ds_read_b32 v102, v102

	s_mov_b64 s[46:47], -1
	s_waitcnt lgkmcnt(0)
	v_cmp_ne_u32_e32 vcc, s5, v102
	s_and_saveexec_b64 s[44:45], vcc
	s_cbranch_execz .LBB0_414
	v_mov_b64_e32 v[102:103], s[8:9]
	s_sleep 1
	ds_read_b32 v102, v102

	s_mov_b64 s[50:51], -1
	s_waitcnt lgkmcnt(0)
	v_cmp_ne_u32_e32 vcc, s5, v102
	s_and_saveexec_b64 s[46:47], vcc
	s_cbranch_execz .LBB0_413
	v_mov_b64_e32 v[102:103], s[8:9]
	s_sleep 1
	ds_read_b32 v102, v102

	s_mov_b64 s[52:53], -1
	s_waitcnt lgkmcnt(0)
	v_cmp_ne_u32_e32 vcc, s5, v102
	s_and_saveexec_b64 s[50:51], vcc
	s_cbranch_execz .LBB0_412
	v_mov_b64_e32 v[102:103], s[8:9]
	s_sleep 1
	ds_read_b32 v102, v102

	s_cmp_lg_u32 s74, 0
	s_cselect_b64 s[52:53], -1, 0
	s_mov_b64 s[54:55], -1
	s_waitcnt lgkmcnt(0)
	v_cmp_ne_u32_e32 vcc, s5, v102
	s_and_b64 s[76:77], vcc, s[52:53]
	s_and_saveexec_b64 s[52:53], s[76:77]
	s_cbranch_execz .LBB0_411
	v_mov_b64_e32 v[102:103], s[8:9]
	s_sleep 1
	ds_read_b32 v102, v102

	s_add_i32 s74, s74, -8
	s_waitcnt lgkmcnt(0)
	v_cmp_eq_u32_e32 vcc, s5, v102
	s_orn2_b64 s[54:55], vcc, exec
	s_branch .LBB0_411
.LBB0_426:
	s_or_b64 exec, exec, s[10:11]
	s_mulk_i32 s73, 0x3000
	v_add_u32_e32 v102, s73, v101
	s_and_b64 vcc, exec, s[6:7]
	s_cbranch_vccz .Lrl_ra_w0
	s_waitcnt vmcnt(12)
	s_branch .Lrl_ra_go

.Lrl_ra_go:
	ds_write_b128 v102, v[4:7]
	ds_write_b128 v102, v[8:11] offset:1024
	ds_write_b128 v102, v[32:35] offset:2048
	ds_write_b128 v102, v[12:15] offset:3072
	ds_write_b128 v102, v[16:19] offset:4096
	ds_write_b128 v102, v[20:23] offset:5120
	ds_write_b128 v102, v[24:27] offset:6144
	ds_write_b128 v102, v[28:31] offset:7168
	ds_write_b128 v102, v[44:47] offset:8192
	ds_write_b128 v102, v[72:75] offset:9216
	ds_write_b128 v102, v[76:79] offset:10240
	ds_write_b128 v102, v[88:91] offset:11264
	s_waitcnt lgkmcnt(0)
	s_and_saveexec_b64 s[10:11], s[38:39]
	s_cbranch_execz .LBB0_428
	s_or_b32 s5, s5, 1
	v_mov_b64_e32 v[102:103], s[8:9]
	v_mov_b32_e32 v104, s5
	ds_write_b32 v102, v104
	s_waitcnt lgkmcnt(0)

.LBB0_431:
	s_mov_b64 s[6:7], src_shared_base
	s_mul_hi_u32 s5, s4, 0xcccccccd
	s_lshr_b32 s6, s5, 3
	s_mul_i32 s5, s6, 10
	s_sub_i32 s72, s4, s5
	s_lshl_b32 s4, s72, 2
	s_add_i32 s4, s4, 0
	s_add_i32 s4, s4, 0x1e000
	s_mov_b32 s5, s7
	v_mov_b64_e32 v[102:103], s[4:5]
	ds_read_b32 v102, v102

	s_lshl_b32 s9, s6, 1
	s_waitcnt lgkmcnt(0)
	v_cmp_ne_u32_e32 vcc, s9, v102
	s_and_saveexec_b64 s[6:7], vcc
	s_cbranch_execz .LBB0_448
	s_mov_b32 s73, 0xffff8
	s_mov_b64 s[20:21], 0
	s_branch .LBB0_440

.LBB0_440:
	v_mov_b64_e32 v[102:103], s[4:5]
	s_sleep 1
	ds_read_b32 v102, v102

	s_or_b64 s[34:35], s[34:35], exec
	s_waitcnt lgkmcnt(0)
	v_cmp_ne_u32_e32 vcc, s9, v102
	s_and_saveexec_b64 s[36:37], vcc
	s_cbranch_execz .LBB0_439
	v_mov_b64_e32 v[102:103], s[4:5]
	s_sleep 1
	ds_read_b32 v102, v102

	s_mov_b64 s[42:43], -1
	s_waitcnt lgkmcnt(0)
	v_cmp_ne_u32_e32 vcc, s9, v102
	s_and_saveexec_b64 s[40:41], vcc
	s_cbranch_execz .LBB0_438
	v_mov_b64_e32 v[102:103], s[4:5]
	s_sleep 1
	ds_read_b32 v102, v102

	s_mov_b64 s[44:45], -1
	s_waitcnt lgkmcnt(0)
	v_cmp_ne_u32_e32 vcc, s9, v102
	s_and_saveexec_b64 s[42:43], vcc
	s_cbranch_execz .LBB0_437
	v_mov_b64_e32 v[102:103], s[4:5]
	s_sleep 1
	ds_read_b32 v102, v102

	s_mov_b64 s[46:47], -1
	s_waitcnt lgkmcnt(0)
	v_cmp_ne_u32_e32 vcc, s9, v102
	s_and_saveexec_b64 s[44:45], vcc
	s_cbranch_execz .LBB0_436
	v_mov_b64_e32 v[102:103], s[4:5]
	s_sleep 1
	ds_read_b32 v102, v102

	s_mov_b64 s[50:51], -1
	s_waitcnt lgkmcnt(0)
	v_cmp_ne_u32_e32 vcc, s9, v102
	s_and_saveexec_b64 s[46:47], vcc
	s_cbranch_execz .LBB0_435
	v_mov_b64_e32 v[102:103], s[4:5]
	s_sleep 1
	ds_read_b32 v102, v102

	s_mov_b64 s[52:53], -1
	s_waitcnt lgkmcnt(0)
	v_cmp_ne_u32_e32 vcc, s9, v102
	s_and_saveexec_b64 s[50:51], vcc
	s_cbranch_execz .LBB0_434
	v_mov_b64_e32 v[102:103], s[4:5]
	s_sleep 1
	ds_read_b32 v102, v102

	s_cmp_lg_u32 s73, 0
	s_cselect_b64 s[52:53], -1, 0
	s_mov_b64 s[54:55], -1
	s_waitcnt lgkmcnt(0)
	v_cmp_ne_u32_e32 vcc, s9, v102
	s_and_b64 s[74:75], vcc, s[52:53]
	s_and_saveexec_b64 s[52:53], s[74:75]
	s_cbranch_execz .LBB0_433
	v_mov_b64_e32 v[102:103], s[4:5]
	s_sleep 1
	ds_read_b32 v102, v102

	s_add_i32 s73, s73, -8
	s_waitcnt lgkmcnt(0)
	v_cmp_eq_u32_e32 vcc, s9, v102
	s_orn2_b64 s[54:55], vcc, exec
	s_branch .LBB0_433
.LBB0_448:
	s_or_b64 exec, exec, s[6:7]
	s_mulk_i32 s72, 0x3000
	v_add_u32_e32 v102, s72, v101
	s_and_b64 vcc, exec, s[10:11]
	s_cbranch_vccnz .Lrl_rb_w0
	s_waitcnt vmcnt(12)
	s_branch .Lrl_rb_go

.Lrl_rb_go:
	ds_write_b128 v102, v[40:43]
	ds_write_b128 v102, v[36:39] offset:1024
	ds_write_b128 v102, v[52:55] offset:2048
	ds_write_b128 v102, v[48:51] offset:3072
	ds_write_b128 v102, v[60:63] offset:4096
	ds_write_b128 v102, v[56:59] offset:5120
	ds_write_b128 v102, v[68:71] offset:6144
	ds_write_b128 v102, v[64:67] offset:7168
	ds_write_b128 v102, v[80:83] offset:8192
	ds_write_b128 v102, v[84:87] offset:9216
	ds_write_b128 v102, v[92:95] offset:10240
	ds_write_b128 v102, v[96:99] offset:11264
	s_waitcnt lgkmcnt(0)
	s_and_saveexec_b64 s[6:7], s[38:39]
	s_cbranch_execz .LBB0_405
	s_or_b32 s9, s9, 1
	v_mov_b64_e32 v[102:103], s[4:5]
	v_mov_b32_e32 v104, s9
	ds_write_b32 v102, v104
	s_waitcnt lgkmcnt(0)
	s_branch .LBB0_405

.LBB0_454:
	s_mov_b64 s[0:1], src_shared_base
	s_mul_hi_u32 s0, s40, 0xcccccccd
	s_lshr_b32 s4, s0, 3
	s_mul_i32 s0, s4, 10
	s_sub_i32 s52, s40, s0
	s_lshl_b32 s0, s52, 2
	s_add_i32 s0, s0, 0
	s_add_i32 s0, s0, 0x1e000
	v_mov_b64_e32 v[20:21], s[0:1]
	ds_read_b32 v20, v20

	s_lshl_b32 s41, s4, 1
	s_or_b32 s53, s41, 1
	s_waitcnt lgkmcnt(0)
	v_cmp_ne_u32_e32 vcc, s53, v20
	s_and_saveexec_b64 s[4:5], vcc
	s_cbranch_execz .LBB0_471
	s_mov_b32 s54, 0xffff8
	s_mov_b64 s[6:7], 0
	s_branch .LBB0_463

.LBB0_463:
	v_mov_b64_e32 v[20:21], s[0:1]
	s_sleep 1
	ds_read_b32 v20, v20

	s_or_b64 s[8:9], s[8:9], exec
	s_waitcnt lgkmcnt(0)
	v_cmp_ne_u32_e32 vcc, s53, v20
	s_and_saveexec_b64 s[10:11], vcc
	s_cbranch_execz .LBB0_462
	v_mov_b64_e32 v[20:21], s[0:1]
	s_sleep 1
	ds_read_b32 v20, v20

	s_mov_b64 s[34:35], -1
	s_waitcnt lgkmcnt(0)
	v_cmp_ne_u32_e32 vcc, s53, v20
	s_and_saveexec_b64 s[20:21], vcc
	s_cbranch_execz .LBB0_461
	v_mov_b64_e32 v[20:21], s[0:1]
	s_sleep 1
	ds_read_b32 v20, v20

	s_mov_b64 s[36:37], -1
	s_waitcnt lgkmcnt(0)
	v_cmp_ne_u32_e32 vcc, s53, v20
	s_and_saveexec_b64 s[34:35], vcc
	s_cbranch_execz .LBB0_460
	v_mov_b64_e32 v[20:21], s[0:1]
	s_sleep 1
	ds_read_b32 v20, v20

	s_mov_b64 s[42:43], -1
	s_waitcnt lgkmcnt(0)
	v_cmp_ne_u32_e32 vcc, s53, v20
	s_and_saveexec_b64 s[36:37], vcc
	s_cbranch_execz .LBB0_459
	v_mov_b64_e32 v[20:21], s[0:1]
	s_sleep 1
	ds_read_b32 v20, v20

	s_mov_b64 s[44:45], -1
	s_waitcnt lgkmcnt(0)
	v_cmp_ne_u32_e32 vcc, s53, v20
	s_and_saveexec_b64 s[42:43], vcc
	s_cbranch_execz .LBB0_458
	v_mov_b64_e32 v[20:21], s[0:1]
	s_sleep 1
	ds_read_b32 v20, v20

	s_mov_b64 s[46:47], -1
	s_waitcnt lgkmcnt(0)
	v_cmp_ne_u32_e32 vcc, s53, v20
	s_and_saveexec_b64 s[44:45], vcc
	s_cbranch_execz .LBB0_457
	v_mov_b64_e32 v[20:21], s[0:1]
	s_sleep 1
	ds_read_b32 v20, v20

	s_cmp_lg_u32 s54, 0
	s_cselect_b64 s[46:47], -1, 0
	s_mov_b64 s[50:51], -1
	s_waitcnt lgkmcnt(0)
	v_cmp_ne_u32_e32 vcc, s53, v20
	s_and_b64 s[70:71], vcc, s[46:47]
	s_and_saveexec_b64 s[46:47], s[70:71]
	s_cbranch_execz .LBB0_456
	v_mov_b64_e32 v[20:21], s[0:1]
	s_sleep 1
	ds_read_b32 v20, v20

	s_add_i32 s54, s54, -8
	s_waitcnt lgkmcnt(0)
	v_cmp_eq_u32_e32 vcc, s53, v20
	s_orn2_b64 s[50:51], vcc, exec
	s_branch .LBB0_456
.LBB0_471:
	s_or_b64 exec, exec, s[4:5]
	s_mulk_i32 s52, 0x3000
	v_add_u32_e32 v24, s52, v2
	ds_read_b128 v[60:63], v24
	ds_read_b128 v[28:31], v24 offset:1024
	ds_read_b128 v[64:67], v24 offset:8192
	ds_read_b128 v[48:51], v24 offset:9216
	ds_read_b128 v[52:55], v24 offset:2048
	ds_read_b128 v[32:35], v24 offset:3072
	ds_read_b128 v[36:39], v24 offset:4096
	ds_read_b128 v[20:23], v24 offset:5120
	ds_read_b128 v[56:59], v24 offset:10240
	ds_read_b128 v[40:43], v24 offset:11264
	ds_read_b128 v[44:47], v24 offset:6144
	ds_read_b128 v[24:27], v24 offset:7168
	s_waitcnt lgkmcnt(0)
	s_and_saveexec_b64 s[4:5], s[38:39]
	s_cbranch_execz .LBB0_453
	s_add_i32 s6, s41, 2
	v_mov_b64_e32 v[72:73], s[0:1]
	v_mov_b32_e32 v74, s6
	ds_write_b32 v72, v74
	s_waitcnt lgkmcnt(0)
	s_branch .LBB0_453
